# opt5
# baseline (speedup 1.0000x reference)
; __device__ __forceinline__ void attention_block(const P& p, int blk) {
;     ...
;   for (int kvh = 0; kvh < 4; ++kvh) {
;     __syncthreads();
; #pragma unroll
;     for (int i = 0; i < 6; ++i) {
;       const int idx = tid + 512 * i, row = idx >> 3, c = idx & 7, key = P0 - 128 + row;
;       uint4 v = make_uint4(0u, 0u, 0u, 0u);
;       if (key >= 0) v = *(const uint4*)(kbuf + (size_t)key * 256 + kvh * 64 + c * 8);
;       *(uint4*)(Kl + row * AK_STRIDE + c * 16) = v;
;     }
; #pragma unroll
;     for (int i = 0; i < 6; ++i) {
;       const int idx = tid + 512 * i, d = idx / 48, c = idx - d * 48, key0 = P0 - 128 + c * 8;
;       uint4 v = make_uint4(0u, 0u, 0u, 0u);
;       if (key0 >= 0) v = *(const uint4*)(vT + (size_t)(kvh * 64 + d) * SEQ + key0);
;       *(uint4*)(Vl + d * AV_STRIDE + c * 16) = v;
;     }
;     if (tid < 256) {
;       const int row = tid >> 3, c = tid & 7;
;       *(uint4*)(Kl + (384 + row) * AK_STRIDE + c * 16) = *(const uint4*)(kmeta + (size_t)row * 256 + kvh * 64 + c * 8);
;       const int d = tid >> 2, c4 = tid & 3;
;       *(uint4*)(Vl + d * AV_STRIDE + 768 + c4 * 16) = *(const uint4*)(vtmeta + (size_t)(kvh * 64 + d) * 32 + c4 * 8);
;     }
.LBB0_290:
	s_lshl_b32 s82, s1, 7
	v_lshl_add_u64 v[8:9], v[140:141], 0, s[82:83]
	s_lshl_b32 s34, s1, 6
	s_barrier
	v_mov_b32_e32 v12, 0
	v_mov_b32_e32 v13, 0
	v_mov_b32_e32 v14, 0
	v_mov_b32_e32 v15, 0
	v_mov_b32_e32 v16, 0
	v_mov_b32_e32 v17, 0
	v_mov_b32_e32 v18, 0
	v_mov_b32_e32 v19, 0
	v_mov_b32_e32 v20, 0
	v_mov_b32_e32 v21, 0
	v_mov_b32_e32 v22, 0
	v_mov_b32_e32 v23, 0
	v_mov_b32_e32 v24, 0
	v_mov_b32_e32 v25, 0
	v_mov_b32_e32 v26, 0
	v_mov_b32_e32 v27, 0
	v_mov_b32_e32 v28, 0
	v_mov_b32_e32 v29, 0
	v_mov_b32_e32 v30, 0
	v_mov_b32_e32 v31, 0
	v_mov_b32_e32 v32, 0
	v_mov_b32_e32 v33, 0
	v_mov_b32_e32 v34, 0
	v_mov_b32_e32 v35, 0
	v_mov_b32_e32 v36, 0
	v_mov_b32_e32 v37, 0
	v_mov_b32_e32 v38, 0
	v_mov_b32_e32 v39, 0
	v_mov_b32_e32 v40, 0
	v_mov_b32_e32 v41, 0
	v_mov_b32_e32 v42, 0
	v_mov_b32_e32 v43, 0
	v_mov_b32_e32 v44, 0
	v_mov_b32_e32 v45, 0
	v_mov_b32_e32 v46, 0
	v_mov_b32_e32 v47, 0
	v_mov_b32_e32 v48, 0
	v_mov_b32_e32 v49, 0
	v_mov_b32_e32 v50, 0
	v_mov_b32_e32 v51, 0
	v_mov_b32_e32 v52, 0
	v_mov_b32_e32 v53, 0
	v_mov_b32_e32 v54, 0
	v_mov_b32_e32 v55, 0
	v_mov_b32_e32 v56, 0
	v_mov_b32_e32 v57, 0
	v_mov_b32_e32 v58, 0
	v_mov_b32_e32 v59, 0
	s_and_saveexec_b64 s[30:31], s[6:7]
	v_lshl_add_u64 v[2:3], v[8:9], 0, v[154:155]
	global_load_dwordx4 v[12:15], v[2:3], off
	s_or_b64 exec, exec, s[30:31]
	s_and_saveexec_b64 s[30:31], s[8:9]
	v_lshl_add_u64 v[2:3], v[8:9], 0, v[156:157]
	global_load_dwordx4 v[16:19], v[2:3], off
	s_or_b64 exec, exec, s[30:31]
	s_and_saveexec_b64 s[30:31], s[10:11]
	v_lshl_add_u64 v[2:3], v[8:9], 0, v[158:159]
	global_load_dwordx4 v[20:23], v[2:3], off
	s_or_b64 exec, exec, s[30:31]
	s_and_saveexec_b64 s[30:31], s[12:13]
	v_lshl_add_u64 v[2:3], v[8:9], 0, v[160:161]
	global_load_dwordx4 v[24:27], v[2:3], off
	s_or_b64 exec, exec, s[30:31]
	s_and_saveexec_b64 s[30:31], s[14:15]
	v_lshl_add_u64 v[2:3], v[8:9], 0, v[162:163]
	global_load_dwordx4 v[28:31], v[2:3], off
	s_or_b64 exec, exec, s[30:31]
	s_and_saveexec_b64 s[30:31], s[16:17]
	v_lshl_add_u64 v[2:3], v[8:9], 0, v[164:165]
	global_load_dwordx4 v[32:35], v[2:3], off
	s_or_b64 exec, exec, s[30:31]
	s_and_saveexec_b64 s[30:31], s[18:19]
	v_add_u32_e32 v2, s34, v198
	v_ashrrev_i32_e32 v3, 31, v2
	v_lshlrev_b64 v[2:3], 12, v[2:3]
	v_lshl_add_u64 v[2:3], v[166:167], 0, v[2:3]
	global_load_dwordx4 v[36:39], v[2:3], off
	s_or_b64 exec, exec, s[30:31]
	s_and_saveexec_b64 s[30:31], s[20:21]
	v_add_u32_e32 v2, s34, v199
	v_ashrrev_i32_e32 v3, 31, v2
	v_lshlrev_b64 v[2:3], 12, v[2:3]
	v_lshl_add_u64 v[2:3], v[168:169], 0, v[2:3]
	global_load_dwordx4 v[40:43], v[2:3], off
	s_or_b64 exec, exec, s[30:31]
	s_and_saveexec_b64 s[30:31], s[22:23]
	v_add_u32_e32 v2, s34, v200
	v_ashrrev_i32_e32 v3, 31, v2
	v_lshlrev_b64 v[2:3], 12, v[2:3]
	v_lshl_add_u64 v[2:3], v[170:171], 0, v[2:3]
	global_load_dwordx4 v[44:47], v[2:3], off
	s_or_b64 exec, exec, s[30:31]
	s_and_saveexec_b64 s[30:31], s[24:25]
	v_add_u32_e32 v2, s34, v201
	v_ashrrev_i32_e32 v3, 31, v2
	v_lshlrev_b64 v[2:3], 12, v[2:3]
	v_lshl_add_u64 v[2:3], v[172:173], 0, v[2:3]
	global_load_dwordx4 v[48:51], v[2:3], off
	s_or_b64 exec, exec, s[30:31]
	s_and_saveexec_b64 s[30:31], s[26:27]
	v_add_u32_e32 v2, s34, v202
	v_ashrrev_i32_e32 v3, 31, v2
	v_lshlrev_b64 v[2:3], 12, v[2:3]
	v_lshl_add_u64 v[2:3], v[174:175], 0, v[2:3]
	global_load_dwordx4 v[52:55], v[2:3], off
	s_or_b64 exec, exec, s[30:31]
	s_and_saveexec_b64 s[30:31], s[28:29]
	v_add_u32_e32 v2, s34, v203
	v_ashrrev_i32_e32 v3, 31, v2
	v_lshlrev_b64 v[2:3], 12, v[2:3]
	v_lshl_add_u64 v[2:3], v[176:177], 0, v[2:3]
	global_load_dwordx4 v[56:59], v[2:3], off
	s_or_b64 exec, exec, s[30:31]
	s_and_saveexec_b64 s[30:31], s[4:5]
	s_cbranch_execz .Lattn_nometa
	v_add_u32_e32 v4, s34, v196
	v_ashrrev_i32_e32 v5, 31, v4
	s_lshl_b32 s82, s34, 1
	v_lshlrev_b64 v[4:5], 6, v[4:5]
	v_lshl_add_u64 v[2:3], v[150:151], 0, s[82:83]
	v_lshl_add_u64 v[6:7], v[152:153], 0, v[4:5]
	global_load_dwordx4 v[2:5], v[2:3], off
	s_nop 0
	global_load_dwordx4 v[6:9], v[6:7], off
.Lattn_nometa:
	s_or_b64 exec, exec, s[30:31]
	v_add_u32_e32 v10, v190, v194
	s_waitcnt vmcnt(11)
	ds_write_b128 v10, v[12:15]
	s_waitcnt vmcnt(10)
	ds_write_b128 v205, v[16:19]
	s_waitcnt vmcnt(9)
	ds_write_b128 v206, v[20:23]
	s_waitcnt vmcnt(8)
	ds_write_b128 v207, v[24:27]
	s_waitcnt vmcnt(7)
	ds_write_b128 v208, v[28:31]
	s_waitcnt vmcnt(6)
	ds_write_b128 v209, v[32:35]
	s_waitcnt vmcnt(5)
	ds_write_b128 v210, v[36:39] offset:59904
	s_waitcnt vmcnt(4)
	ds_write_b128 v211, v[40:43] offset:59904
	s_waitcnt vmcnt(3)
	ds_write_b128 v212, v[44:47] offset:59904
	s_waitcnt vmcnt(2)
	ds_write_b128 v213, v[48:51] offset:59904
	s_waitcnt vmcnt(1)
	ds_write_b128 v214, v[52:55] offset:59904
	s_waitcnt vmcnt(0)
	ds_write_b128 v215, v[56:59] offset:59904
	s_and_saveexec_b64 s[30:31], s[4:5]
	ds_write_b128 v195, v[2:5]
	ds_write_b128 v197, v[6:9]
